# stack: + QK/up epilogue row-scale loads hoisted to the tile's K-loop entry (no VMEM waits inside the epilogue); + redundant canonicalize v_max removed in the up epilogue
# speedup vs baseline: 1.0014x; 1.0014x over previous
; template <class Epi, class Sched, bool ALIGN_EPI = false, bool SP2 = false>
; __device__ __forceinline__ void gemm_phase(PG8_LAS unsigned char* lds, const Gemm g, const Sched& S, const Epi& E) {
;     ...
;     for (;;) {
;         const bool has_next = S.next(ui + 1, nxt);
;         const char* nA = has_next ? (const char*)g.A + (size_t)nxt.pm * tstep : cA; const char* nB = has_next ? (const char*)g.Bt + (size_t)nxt.pn * tstep : cB;
;         for (int t = 0; t < nt; t += 2) {
;     ...
; #pragma unroll
;         for (int a = 0; a < 2; ++a)
; #pragma unroll
;             for (int b = 0; b < 2; ++b)
; #pragma unroll
;                 for (int m = 0; m < 4; ++m)
; #pragma unroll
;                     for (int n = 0; n < 2; ++n) acc[a][b][m][n] = (f32x4){0.f, 0.f, 0.f, 0.f};
.LBB0_211:
	s_ashr_i32 s89, s88, 31
	s_lshl_b64 s[4:5], s[88:89], 20
	s_add_u32 s4, s22, s4
	s_addc_u32 s5, s75, s5
	s_and_b64 s[6:7], s[38:39], exec
	s_cselect_b32 s89, s5, s9
	s_cselect_b32 vcc_lo, s4, s8
	s_ashr_i32 s73, s72, 31
	s_lshl_b64 s[6:7], s[72:73], 20
	s_add_u32 s6, s68, s6
	s_addc_u32 s7, s69, s7
	s_and_b64 s[16:17], s[38:39], exec
	s_cselect_b32 s70, s7, s11
	s_cselect_b32 s71, s6, s10
	s_add_u32 s73, s10, 0x100
	v_mov_b32_e32 v0, 0
	s_addc_u32 vcc_hi, s11, 0
	s_mov_b32 s52, -2
	s_mov_b64 s[10:11], 0
	v_mov_b32_e32 v1, v0
	v_mov_b32_e32 v2, v0
	v_mov_b32_e32 v3, v0
	v_mov_b32_e32 v4, v0
	v_mov_b32_e32 v5, v0
	v_mov_b32_e32 v6, v0
	v_mov_b32_e32 v7, v0
	v_mov_b32_e32 v16, v0
	v_mov_b32_e32 v17, v0
	v_mov_b32_e32 v18, v0
	v_mov_b32_e32 v19, v0
	v_mov_b32_e32 v20, v0
	v_mov_b32_e32 v21, v0
	v_mov_b32_e32 v22, v0
	v_mov_b32_e32 v23, v0
	v_mov_b32_e32 v32, v0
	v_mov_b32_e32 v33, v0
	v_mov_b32_e32 v34, v0
	v_mov_b32_e32 v35, v0
	v_mov_b32_e32 v36, v0
	v_mov_b32_e32 v37, v0
	v_mov_b32_e32 v38, v0
	v_mov_b32_e32 v39, v0
	v_mov_b32_e32 v48, v0
	v_mov_b32_e32 v49, v0
	v_mov_b32_e32 v50, v0
	v_mov_b32_e32 v51, v0
	v_mov_b32_e32 v52, v0
	v_mov_b32_e32 v53, v0
	v_mov_b32_e32 v54, v0
	v_mov_b32_e32 v55, v0
	v_mov_b32_e32 v8, v0
	v_mov_b32_e32 v9, v0
	v_mov_b32_e32 v10, v0
	v_mov_b32_e32 v11, v0
	v_mov_b32_e32 v12, v0
	v_mov_b32_e32 v13, v0
	v_mov_b32_e32 v14, v0
	v_mov_b32_e32 v15, v0
	v_mov_b32_e32 v24, v0
	v_mov_b32_e32 v25, v0
	v_mov_b32_e32 v26, v0
	v_mov_b32_e32 v27, v0
	v_mov_b32_e32 v28, v0
	v_mov_b32_e32 v29, v0
	v_mov_b32_e32 v30, v0
	v_mov_b32_e32 v31, v0
	v_mov_b32_e32 v40, v0
	v_mov_b32_e32 v41, v0
	v_mov_b32_e32 v42, v0
	v_mov_b32_e32 v43, v0
	v_mov_b32_e32 v44, v0
	v_mov_b32_e32 v45, v0
	v_mov_b32_e32 v46, v0
	v_mov_b32_e32 v47, v0
	v_mov_b32_e32 v56, v0
	v_mov_b32_e32 v57, v0
	v_mov_b32_e32 v58, v0
	v_mov_b32_e32 v59, v0
	v_mov_b32_e32 v60, v0
	v_mov_b32_e32 v61, v0
	v_mov_b32_e32 v62, v0
	v_mov_b32_e32 v63, v0
	v_mov_b32_e32 v64, v0
	v_mov_b32_e32 v65, v0
	v_mov_b32_e32 v66, v0
	v_mov_b32_e32 v67, v0
	v_mov_b32_e32 v68, v0
	v_mov_b32_e32 v69, v0
	v_mov_b32_e32 v70, v0
	v_mov_b32_e32 v71, v0
	v_mov_b32_e32 v80, v0
	v_mov_b32_e32 v81, v0
	v_mov_b32_e32 v82, v0
	v_mov_b32_e32 v83, v0
	v_mov_b32_e32 v84, v0
	v_mov_b32_e32 v85, v0
	v_mov_b32_e32 v86, v0
	v_mov_b32_e32 v87, v0
	v_mov_b32_e32 v96, v0
	v_mov_b32_e32 v97, v0
	v_mov_b32_e32 v98, v0
	v_mov_b32_e32 v99, v0
	v_mov_b32_e32 v100, v0
	v_mov_b32_e32 v101, v0
	v_mov_b32_e32 v102, v0
	v_mov_b32_e32 v103, v0
	v_mov_b32_e32 v112, v0
	v_mov_b32_e32 v113, v0
	v_mov_b32_e32 v114, v0
	v_mov_b32_e32 v115, v0
	v_mov_b32_e32 v116, v0
	v_mov_b32_e32 v117, v0
	v_mov_b32_e32 v118, v0
	v_mov_b32_e32 v119, v0
	v_mov_b32_e32 v72, v0
	v_mov_b32_e32 v73, v0
	v_mov_b32_e32 v74, v0
	v_mov_b32_e32 v75, v0
	v_mov_b32_e32 v76, v0
	v_mov_b32_e32 v77, v0
	v_mov_b32_e32 v78, v0
	v_mov_b32_e32 v79, v0
	v_mov_b32_e32 v88, v0
	v_mov_b32_e32 v89, v0
	v_mov_b32_e32 v90, v0
	v_mov_b32_e32 v91, v0
	v_mov_b32_e32 v92, v0
	v_mov_b32_e32 v93, v0
	v_mov_b32_e32 v94, v0
	v_mov_b32_e32 v95, v0
	v_mov_b32_e32 v104, v0
	v_mov_b32_e32 v105, v0
	v_mov_b32_e32 v106, v0
	v_mov_b32_e32 v107, v0
	v_mov_b32_e32 v108, v0
	v_mov_b32_e32 v109, v0
	v_mov_b32_e32 v110, v0
	v_mov_b32_e32 v111, v0
	v_mov_b32_e32 v120, v0
	v_mov_b32_e32 v121, v0
	v_mov_b32_e32 v122, v0
	v_mov_b32_e32 v123, v0
	v_mov_b32_e32 v124, v0
	v_mov_b32_e32 v125, v0
	v_mov_b32_e32 v126, v0
	v_mov_b32_e32 v127, v0
	v_lshl_add_u64 v[138:139], s[8:9], 0, v[134:135]
	v_lshl_add_u64 v[140:141], s[8:9], 0, v[136:137]
	v_lshl_add_u32 v240, s35, 8, v146
	v_ashrrev_i32_e32 v241, 31, v240
	v_lshl_add_u64 v[240:241], v[240:241], 2, s[42:43]
	global_load_dword v242, v[240:241], off
	global_load_dword v243, v[240:241], off offset:64
	global_load_dword v244, v[240:241], off offset:128
	global_load_dword v245, v[240:241], off offset:192
	global_load_dword v246, v[240:241], off offset:512
	global_load_dword v247, v[240:241], off offset:576
	global_load_dword v248, v[240:241], off offset:640
	global_load_dword v249, v[240:241], off offset:704

; __device__ __forceinline__ unsigned cvt_pk_bf16(float lo, float hi) { unsigned r; asm volatile("v_cvt_pk_bf16_f32 %0, %1, %2" : "=v"(r) : "v"(lo), "v"(hi)); return r; }
;     __device__ __forceinline__ void operator()(const f32x4 (&acc)[2][2][4][2], const Unit& u, int wr, int wc, int fr, int fq) const {
;         const int row0 = u.pm * BM + wr * 64 + fr; const int colt = u.pn * BM;
;         const float sc = (colt < scale_cols) ? scale0 : 1.f;
;         const int col0 = colt + wc * 32 + 8 * fq;
;         f32x4 cs[2][2];
; #pragma unroll
;         for (int bj = 0; bj < 2; ++bj) { cs[bj][0] = (f32x4){1.f, 1.f, 1.f, 1.f}; cs[bj][1] = cs[bj][0]; if (rsmode == 2) { cs[bj][0] = *(const f32x4*)(rs + col0 + bj * HALF); cs[bj][1] = *(const f32x4*)(rs + col0 + bj * HALF + 4); } }
; #pragma unroll
;         for (int ai = 0; ai < 2; ++ai)
; #pragma unroll
;             for (int m = 0; m < 4; ++m) { bf16_t* rowp = O + (size_t)(row0 + ai * HALF + m * 16) * ldc + col0;
;                 float rsc = sc; if (rsmode == 1) { const float r_ = rs[row0 + ai * HALF + m * 16]; rsc = sc * (ACT == 2 ? r_ * r_ : r_); }
; #pragma unroll
;                 for (int bj = 0; bj < 2; ++bj) { f32x4 v0 = acc[ai][bj][m][0], v1 = acc[ai][bj][m][1];
;                     if (ACT == 2) {
; #pragma unroll
;                         for (int e = 0; e < 4; ++e) { const float a0 = fmaxf(v0[e], 0.f), a1 = fmaxf(v1[e], 0.f); v0[e] = a0 * a0; v1[e] = a1 * a1; } }
;                     v0 = v0 * cs[bj][0] * rsc; v1 = v1 * cs[bj][1] * rsc; u32x4 w; w.x = cvt_pk_bf16(v0[0], v0[1]); w.y = cvt_pk_bf16(v0[2], v0[3]); w.z = cvt_pk_bf16(v1[0], v1[1]); w.w = cvt_pk_bf16(v1[2], v1[3]);
;                     *(u32x4*)(rowp + bj * HALF) = w; } }
.LBB0_215:
	v_lshl_add_u32 v142, s35, 8, v146
	v_lshl_or_b32 v138, s34, 8, v148
	v_ashrrev_i32_e32 v143, 31, v142
	v_ashrrev_i32_e32 v139, 31, v138
	v_lshlrev_b64 v[140:141], 13, v[142:143]
	v_lshl_add_u64 v[140:141], s[94:95], 0, v[140:141]
	v_lshlrev_b64 v[144:145], 1, v[138:139]
	v_lshl_add_u64 v[138:139], v[140:141], 0, v[144:145]
	v_lshl_add_u64 v[140:141], v[142:143], 2, s[42:43]
	s_nop 0
	s_cmp_lt_i32 s34, 8
	s_cselect_b64 vcc, -1, 0
	v_cndmask_b32_e32 v150, 1.0, v228, vcc
	s_mov_b32 s8, 0x100000
	v_mul_f32_e32 v152, v150, v242
	v_pk_mul_f32 v[126:127], v[126:127], v[152:153] op_sel_hi:[1,0]
	v_pk_mul_f32 v[124:125], v[124:125], v[152:153] op_sel_hi:[1,0]
	v_pk_mul_f32 v[154:155], v[122:123], v[152:153] op_sel_hi:[1,0]
	v_pk_mul_f32 v[122:123], v[120:121], v[152:153] op_sel_hi:[1,0]
	v_cvt_pk_bf16_f32 v120, v124, v125
	v_cvt_pk_bf16_f32 v121, v126, v127
	v_pk_mul_f32 v[116:117], v[116:117], v[152:153] op_sel_hi:[1,0]
	v_cvt_pk_bf16_f32 v122, v122, v123
	v_cvt_pk_bf16_f32 v123, v154, v155
	global_store_dwordx4 v[138:139], v[120:123], off
	v_pk_mul_f32 v[118:119], v[118:119], v[152:153] op_sel_hi:[1,0]
	s_nop 0
	v_pk_mul_f32 v[120:121], v[114:115], v[152:153] op_sel_hi:[1,0]
	v_pk_mul_f32 v[114:115], v[112:113], v[152:153] op_sel_hi:[1,0]
	v_cvt_pk_bf16_f32 v112, v116, v117
	v_cvt_pk_bf16_f32 v113, v118, v119
	s_nop 0
	v_cvt_pk_bf16_f32 v114, v114, v115
	v_cvt_pk_bf16_f32 v115, v120, v121
	global_store_dwordx4 v[138:139], v[112:115], off offset:256
	s_nop 1
	v_or_b32_e32 v112, 16, v142
	v_ashrrev_i32_e32 v113, 31, v112
	v_lshlrev_b64 v[114:115], 13, v[112:113]
	v_lshl_add_u64 v[112:113], v[112:113], 2, s[42:43]
	s_nop 0
	v_lshl_add_u64 v[114:115], s[94:95], 0, v[114:115]
	v_lshl_add_u64 v[114:115], v[114:115], 0, v[144:145]
	v_mul_f32_e32 v112, v150, v243
	v_pk_mul_f32 v[110:111], v[110:111], v[112:113] op_sel_hi:[1,0]
	v_pk_mul_f32 v[108:109], v[108:109], v[112:113] op_sel_hi:[1,0]
	v_pk_mul_f32 v[116:117], v[106:107], v[112:113] op_sel_hi:[1,0]
	v_pk_mul_f32 v[106:107], v[104:105], v[112:113] op_sel_hi:[1,0]
	v_cvt_pk_bf16_f32 v104, v108, v109
	v_cvt_pk_bf16_f32 v105, v110, v111
	v_pk_mul_f32 v[100:101], v[100:101], v[112:113] op_sel_hi:[1,0]
	v_cvt_pk_bf16_f32 v106, v106, v107
	v_cvt_pk_bf16_f32 v107, v116, v117
	global_store_dwordx4 v[114:115], v[104:107], off
	v_pk_mul_f32 v[102:103], v[102:103], v[112:113] op_sel_hi:[1,0]
	s_nop 0
	v_pk_mul_f32 v[104:105], v[98:99], v[112:113] op_sel_hi:[1,0]
	v_pk_mul_f32 v[98:99], v[96:97], v[112:113] op_sel_hi:[1,0]
	v_cvt_pk_bf16_f32 v96, v100, v101
	v_cvt_pk_bf16_f32 v97, v102, v103
	s_nop 0
	v_cvt_pk_bf16_f32 v98, v98, v99
	v_cvt_pk_bf16_f32 v99, v104, v105
	global_store_dwordx4 v[114:115], v[96:99], off offset:256
	s_nop 1
	v_or_b32_e32 v96, 32, v142
	v_ashrrev_i32_e32 v97, 31, v96
	v_lshlrev_b64 v[98:99], 13, v[96:97]
	v_lshl_add_u64 v[96:97], v[96:97], 2, s[42:43]
	s_nop 0
	v_lshl_add_u64 v[98:99], s[94:95], 0, v[98:99]
	v_lshl_add_u64 v[98:99], v[98:99], 0, v[144:145]
	v_mul_f32_e32 v96, v150, v244
	v_pk_mul_f32 v[94:95], v[94:95], v[96:97] op_sel_hi:[1,0]
	v_pk_mul_f32 v[92:93], v[92:93], v[96:97] op_sel_hi:[1,0]
	v_pk_mul_f32 v[100:101], v[90:91], v[96:97] op_sel_hi:[1,0]
	v_pk_mul_f32 v[90:91], v[88:89], v[96:97] op_sel_hi:[1,0]
	v_cvt_pk_bf16_f32 v88, v92, v93
	v_cvt_pk_bf16_f32 v89, v94, v95
	v_pk_mul_f32 v[84:85], v[84:85], v[96:97] op_sel_hi:[1,0]
	v_cvt_pk_bf16_f32 v90, v90, v91
	v_cvt_pk_bf16_f32 v91, v100, v101
	global_store_dwordx4 v[98:99], v[88:91], off
	v_pk_mul_f32 v[86:87], v[86:87], v[96:97] op_sel_hi:[1,0]
	s_nop 0
	v_pk_mul_f32 v[88:89], v[82:83], v[96:97] op_sel_hi:[1,0]
	v_pk_mul_f32 v[82:83], v[80:81], v[96:97] op_sel_hi:[1,0]
	v_cvt_pk_bf16_f32 v80, v84, v85
	v_cvt_pk_bf16_f32 v81, v86, v87
	s_nop 0
	v_cvt_pk_bf16_f32 v82, v82, v83
	v_cvt_pk_bf16_f32 v83, v88, v89
	global_store_dwordx4 v[98:99], v[80:83], off offset:256
	s_nop 1
	v_or_b32_e32 v80, 48, v142
	v_ashrrev_i32_e32 v81, 31, v80
	v_lshlrev_b64 v[82:83], 13, v[80:81]
	v_lshl_add_u64 v[80:81], v[80:81], 2, s[42:43]
	s_nop 0
	v_lshl_add_u64 v[82:83], s[94:95], 0, v[82:83]
	v_lshl_add_u64 v[82:83], v[82:83], 0, v[144:145]
	v_mul_f32_e32 v80, v150, v245
	v_pk_mul_f32 v[78:79], v[78:79], v[80:81] op_sel_hi:[1,0]
	v_pk_mul_f32 v[76:77], v[76:77], v[80:81] op_sel_hi:[1,0]
	v_pk_mul_f32 v[84:85], v[74:75], v[80:81] op_sel_hi:[1,0]
	v_pk_mul_f32 v[74:75], v[72:73], v[80:81] op_sel_hi:[1,0]
	v_cvt_pk_bf16_f32 v72, v76, v77
	v_cvt_pk_bf16_f32 v73, v78, v79
	v_pk_mul_f32 v[70:71], v[70:71], v[80:81] op_sel_hi:[1,0]
	v_cvt_pk_bf16_f32 v74, v74, v75
	v_cvt_pk_bf16_f32 v75, v84, v85
	global_store_dwordx4 v[82:83], v[72:75], off
	v_pk_mul_f32 v[68:69], v[68:69], v[80:81] op_sel_hi:[1,0]
	s_nop 0
; __device__ __forceinline__ unsigned cvt_pk_bf16(float lo, float hi) { unsigned r; asm volatile("v_cvt_pk_bf16_f32 %0, %1, %2" : "=v"(r) : "v"(lo), "v"(hi)); return r; }
;     __device__ __forceinline__ void operator()(const f32x4 (&acc)[2][2][4][2], const Unit& u, int wr, int wc, int fr, int fq) const {
;         const int row0 = u.pm * BM + wr * 64 + fr; const int colt = u.pn * BM;
;         const float sc = (colt < scale_cols) ? scale0 : 1.f;
;         const int col0 = colt + wc * 32 + 8 * fq;
;         f32x4 cs[2][2];
; #pragma unroll
;         for (int bj = 0; bj < 2; ++bj) { cs[bj][0] = (f32x4){1.f, 1.f, 1.f, 1.f}; cs[bj][1] = cs[bj][0]; if (rsmode == 2) { cs[bj][0] = *(const f32x4*)(rs + col0 + bj * HALF); cs[bj][1] = *(const f32x4*)(rs + col0 + bj * HALF + 4); } }
; #pragma unroll
;         for (int ai = 0; ai < 2; ++ai)
; #pragma unroll
;             for (int m = 0; m < 4; ++m) { bf16_t* rowp = O + (size_t)(row0 + ai * HALF + m * 16) * ldc + col0;
;                 float rsc = sc; if (rsmode == 1) { const float r_ = rs[row0 + ai * HALF + m * 16]; rsc = sc * (ACT == 2 ? r_ * r_ : r_); }
; #pragma unroll
;                 for (int bj = 0; bj < 2; ++bj) { f32x4 v0 = acc[ai][bj][m][0], v1 = acc[ai][bj][m][1];
;                     if (ACT == 2) {
; #pragma unroll
;                         for (int e = 0; e < 4; ++e) { const float a0 = fmaxf(v0[e], 0.f), a1 = fmaxf(v1[e], 0.f); v0[e] = a0 * a0; v1[e] = a1 * a1; } }
;                     v0 = v0 * cs[bj][0] * rsc; v1 = v1 * cs[bj][1] * rsc; u32x4 w; w.x = cvt_pk_bf16(v0[0], v0[1]); w.y = cvt_pk_bf16(v0[2], v0[3]); w.z = cvt_pk_bf16(v1[0], v1[1]); w.w = cvt_pk_bf16(v1[2], v1[3]);
;                     *(u32x4*)(rowp + bj * HALF) = w; } }
	v_pk_mul_f32 v[72:73], v[66:67], v[80:81] op_sel_hi:[1,0]
	v_pk_mul_f32 v[66:67], v[64:65], v[80:81] op_sel_hi:[1,0]
	v_cvt_pk_bf16_f32 v64, v68, v69
	v_cvt_pk_bf16_f32 v65, v70, v71
	s_nop 0
	v_cvt_pk_bf16_f32 v66, v66, v67
	v_cvt_pk_bf16_f32 v67, v72, v73
	global_store_dwordx4 v[82:83], v[64:67], off offset:256
	s_nop 0
	s_nop 0
	v_lshl_add_u64 v[64:65], v[138:139], 0, s[30:31]
	v_mul_f32_e32 v66, v150, v246
	v_pk_mul_f32 v[60:61], v[60:61], v[66:67] op_sel_hi:[1,0]
	v_pk_mul_f32 v[68:69], v[58:59], v[66:67] op_sel_hi:[1,0]
	v_pk_mul_f32 v[58:59], v[56:57], v[66:67] op_sel_hi:[1,0]
	v_cvt_pk_bf16_f32 v56, v60, v61
	v_add_co_u32_e32 v60, vcc, s8, v138
	v_pk_mul_f32 v[62:63], v[62:63], v[66:67] op_sel_hi:[1,0]
	s_nop 0
	v_addc_co_u32_e32 v61, vcc, 0, v139, vcc
	v_cvt_pk_bf16_f32 v57, v62, v63
	v_cvt_pk_bf16_f32 v58, v58, v59
	v_cvt_pk_bf16_f32 v59, v68, v69
	global_store_dwordx4 v[60:61], v[56:59], off
	v_pk_mul_f32 v[54:55], v[54:55], v[66:67] op_sel_hi:[1,0]
	v_pk_mul_f32 v[52:53], v[52:53], v[66:67] op_sel_hi:[1,0]
	v_pk_mul_f32 v[56:57], v[50:51], v[66:67] op_sel_hi:[1,0]
	v_pk_mul_f32 v[50:51], v[48:49], v[66:67] op_sel_hi:[1,0]
	v_cvt_pk_bf16_f32 v48, v52, v53
	v_cvt_pk_bf16_f32 v49, v54, v55
	s_mov_b64 s[8:9], 0x120000
	v_cvt_pk_bf16_f32 v50, v50, v51
	v_cvt_pk_bf16_f32 v51, v56, v57
	global_store_dwordx4 v[64:65], v[48:51], off offset:256
	s_nop 0
	s_nop 0
	v_lshl_add_u64 v[48:49], v[138:139], 0, s[8:9]
	s_mov_b32 s8, 0x120000
	v_mul_f32_e32 v50, v150, v247
	v_pk_mul_f32 v[44:45], v[44:45], v[50:51] op_sel_hi:[1,0]
	v_pk_mul_f32 v[52:53], v[42:43], v[50:51] op_sel_hi:[1,0]
	v_pk_mul_f32 v[42:43], v[40:41], v[50:51] op_sel_hi:[1,0]
	v_cvt_pk_bf16_f32 v40, v44, v45
	v_add_co_u32_e32 v44, vcc, s8, v138
	v_pk_mul_f32 v[46:47], v[46:47], v[50:51] op_sel_hi:[1,0]
	s_nop 0
	v_addc_co_u32_e32 v45, vcc, 0, v139, vcc
	v_cvt_pk_bf16_f32 v41, v46, v47
	v_cvt_pk_bf16_f32 v42, v42, v43
	v_cvt_pk_bf16_f32 v43, v52, v53
	global_store_dwordx4 v[44:45], v[40:43], off
	v_pk_mul_f32 v[38:39], v[38:39], v[50:51] op_sel_hi:[1,0]
	v_pk_mul_f32 v[36:37], v[36:37], v[50:51] op_sel_hi:[1,0]
	v_pk_mul_f32 v[40:41], v[34:35], v[50:51] op_sel_hi:[1,0]
	v_pk_mul_f32 v[34:35], v[32:33], v[50:51] op_sel_hi:[1,0]
	v_cvt_pk_bf16_f32 v32, v36, v37
	v_cvt_pk_bf16_f32 v33, v38, v39
	s_mov_b64 s[8:9], 0x140000
	v_cvt_pk_bf16_f32 v34, v34, v35
	v_cvt_pk_bf16_f32 v35, v40, v41
	global_store_dwordx4 v[48:49], v[32:35], off offset:256
	s_nop 0
	s_nop 0
	v_lshl_add_u64 v[32:33], v[138:139], 0, s[8:9]
	s_mov_b32 s8, 0x140000
	v_mul_f32_e32 v34, v150, v248
	v_pk_mul_f32 v[28:29], v[28:29], v[34:35] op_sel_hi:[1,0]
	v_pk_mul_f32 v[36:37], v[26:27], v[34:35] op_sel_hi:[1,0]
	v_pk_mul_f32 v[26:27], v[24:25], v[34:35] op_sel_hi:[1,0]
	v_cvt_pk_bf16_f32 v24, v28, v29
	v_add_co_u32_e32 v28, vcc, s8, v138
	v_pk_mul_f32 v[30:31], v[30:31], v[34:35] op_sel_hi:[1,0]
	s_nop 0
	v_addc_co_u32_e32 v29, vcc, 0, v139, vcc
	v_cvt_pk_bf16_f32 v25, v30, v31
	v_cvt_pk_bf16_f32 v26, v26, v27
	v_cvt_pk_bf16_f32 v27, v36, v37
	global_store_dwordx4 v[28:29], v[24:27], off
	v_pk_mul_f32 v[22:23], v[22:23], v[34:35] op_sel_hi:[1,0]
	v_pk_mul_f32 v[20:21], v[20:21], v[34:35] op_sel_hi:[1,0]
	v_pk_mul_f32 v[24:25], v[18:19], v[34:35] op_sel_hi:[1,0]
	v_pk_mul_f32 v[18:19], v[16:17], v[34:35] op_sel_hi:[1,0]
	v_cvt_pk_bf16_f32 v16, v20, v21
	v_cvt_pk_bf16_f32 v17, v22, v23
	s_mov_b64 s[8:9], 0x160000
	v_cvt_pk_bf16_f32 v18, v18, v19
	v_cvt_pk_bf16_f32 v19, v24, v25
	global_store_dwordx4 v[32:33], v[16:19], off offset:256
	s_nop 0
	s_nop 0
	v_lshl_add_u64 v[18:19], v[138:139], 0, s[8:9]
	s_mov_b32 s8, 0x160000
	v_mul_f32_e32 v16, v150, v249
	v_pk_mul_f32 v[12:13], v[12:13], v[16:17] op_sel_hi:[1,0]
	v_pk_mul_f32 v[20:21], v[10:11], v[16:17] op_sel_hi:[1,0]
	v_pk_mul_f32 v[10:11], v[8:9], v[16:17] op_sel_hi:[1,0]
	v_cvt_pk_bf16_f32 v8, v12, v13
	v_add_co_u32_e32 v12, vcc, s8, v138
	v_pk_mul_f32 v[14:15], v[14:15], v[16:17] op_sel_hi:[1,0]
	s_nop 0
	v_addc_co_u32_e32 v13, vcc, 0, v139, vcc
	v_cvt_pk_bf16_f32 v9, v14, v15
	v_cvt_pk_bf16_f32 v10, v10, v11
	v_cvt_pk_bf16_f32 v11, v20, v21
	global_store_dwordx4 v[12:13], v[8:11], off
	s_mov_b64 s[8:9], -1
	s_andn2_b64 vcc, exec, s[38:39]
	v_pk_mul_f32 v[8:9], v[2:3], v[16:17] op_sel_hi:[1,0]
	v_pk_mul_f32 v[2:3], v[0:1], v[16:17] op_sel_hi:[1,0]
	v_pk_mul_f32 v[6:7], v[6:7], v[16:17] op_sel_hi:[1,0]
	v_pk_mul_f32 v[4:5], v[4:5], v[16:17] op_sel_hi:[1,0]
	s_nop 0
	v_cvt_pk_bf16_f32 v0, v4, v5
	v_cvt_pk_bf16_f32 v1, v6, v7
	v_cvt_pk_bf16_f32 v2, v2, v3
	v_cvt_pk_bf16_f32 v3, v8, v9
	global_store_dwordx4 v[18:19], v[0:3], off offset:256
	s_cbranch_vccnz .LBB0_204
	s_andn2_b64 vcc, exec, s[46:47]
	s_cbranch_vccnz .LBB0_203
	s_barrier
	s_branch .LBB0_203

; template <class Epi, class Sched, bool ALIGN_EPI = false, bool SP2 = false>
; __device__ __forceinline__ void gemm_phase(PG8_LAS unsigned char* lds, const Gemm g, const Sched& S, const Epi& E) {
;     ...
;         const bool has_next = S.next(ui + 1, nxt);
;         const char* nA = has_next ? (const char*)g.A + (size_t)nxt.pm * tstep : cA; const char* nB = has_next ? (const char*)g.Bt + (size_t)nxt.pn * tstep : cB;
;         for (int t = 0; t < nt; t += 2) {
;             const bool last = (t == nt - 2);
;             const char* a1 = cA + (size_t)(t + 1) * kstep;
;             const char* a2 = last ? nA : cA + (size_t)(t + 2) * kstep; const char* b2 = last ? nB : cB + (size_t)(t + 2) * kstep;
;     ...
; #pragma unroll
;         for (int a = 0; a < 2; ++a)
; #pragma unroll
;             for (int b = 0; b < 2; ++b)
; #pragma unroll
;                 for (int m = 0; m < 4; ++m)
; #pragma unroll
;                     for (int n = 0; n < 2; ++n) acc[a][b][m][n] = (f32x4){0.f, 0.f, 0.f, 0.f};
.LBB0_604:
	s_ashr_i32 s95, s94, 31
	s_lshl_b64 s[16:17], s[94:95], 20
	s_add_u32 s16, s20, s16
	s_addc_u32 s17, s21, s17
	s_and_b64 s[44:45], s[42:43], exec
	s_cselect_b32 s95, s17, s9
	s_cselect_b32 s70, s16, s8
	s_ashr_i32 s7, s6, 31
	s_lshl_b64 s[44:45], s[6:7], 20
	s_add_u32 s44, s22, s44
	s_addc_u32 s45, s23, s45
	s_and_b64 s[52:53], s[42:43], exec
	s_cselect_b32 s7, s45, s11
	s_cselect_b32 s71, s44, s10
	s_add_u32 s79, s10, 0x100
	v_mov_b32_e32 v0, 0
	v_lshl_add_u64 v[138:139], s[8:9], 0, v[134:135]
	v_lshl_add_u64 v[140:141], s[8:9], 0, v[136:137]
	s_addc_u32 s52, s11, 0
	s_mov_b32 s53, -2
	s_mov_b64 vcc, 0
	v_mov_b32_e32 v1, v0
	v_mov_b32_e32 v2, v0
	v_mov_b32_e32 v3, v0
	v_mov_b32_e32 v4, v0
	v_mov_b32_e32 v5, v0
	v_mov_b32_e32 v6, v0
	v_mov_b32_e32 v7, v0
	v_mov_b32_e32 v16, v0
	v_mov_b32_e32 v17, v0
	v_mov_b32_e32 v18, v0
	v_mov_b32_e32 v19, v0
	v_mov_b32_e32 v20, v0
	v_mov_b32_e32 v21, v0
	v_mov_b32_e32 v22, v0
	v_mov_b32_e32 v23, v0
	v_mov_b32_e32 v32, v0
	v_mov_b32_e32 v33, v0
	v_mov_b32_e32 v34, v0
	v_mov_b32_e32 v35, v0
	v_mov_b32_e32 v36, v0
	v_mov_b32_e32 v37, v0
	v_mov_b32_e32 v38, v0
	v_mov_b32_e32 v39, v0
	v_mov_b32_e32 v48, v0
	v_mov_b32_e32 v49, v0
	v_mov_b32_e32 v50, v0
	v_mov_b32_e32 v51, v0
	v_mov_b32_e32 v52, v0
	v_mov_b32_e32 v53, v0
	v_mov_b32_e32 v54, v0
	v_mov_b32_e32 v55, v0
	v_mov_b32_e32 v8, v0
	v_mov_b32_e32 v9, v0
	v_mov_b32_e32 v10, v0
	v_mov_b32_e32 v11, v0
	v_mov_b32_e32 v12, v0
	v_mov_b32_e32 v13, v0
	v_mov_b32_e32 v14, v0
	v_mov_b32_e32 v15, v0
	v_mov_b32_e32 v24, v0
	v_mov_b32_e32 v25, v0
	v_mov_b32_e32 v26, v0
	v_mov_b32_e32 v27, v0
	v_mov_b32_e32 v28, v0
	v_mov_b32_e32 v29, v0
	v_mov_b32_e32 v30, v0
	v_mov_b32_e32 v31, v0
	v_mov_b32_e32 v40, v0
	v_mov_b32_e32 v41, v0
	v_mov_b32_e32 v42, v0
	v_mov_b32_e32 v43, v0
	v_mov_b32_e32 v44, v0
	v_mov_b32_e32 v45, v0
	v_mov_b32_e32 v46, v0
	v_mov_b32_e32 v47, v0
	v_mov_b32_e32 v56, v0
	v_mov_b32_e32 v57, v0
	v_mov_b32_e32 v58, v0
	v_mov_b32_e32 v59, v0
	v_mov_b32_e32 v60, v0
	v_mov_b32_e32 v61, v0
	v_mov_b32_e32 v62, v0
	v_mov_b32_e32 v63, v0
	v_mov_b32_e32 v64, v0
	v_mov_b32_e32 v65, v0
	v_mov_b32_e32 v66, v0
	v_mov_b32_e32 v67, v0
	v_mov_b32_e32 v68, v0
	v_mov_b32_e32 v69, v0
	v_mov_b32_e32 v70, v0
	v_mov_b32_e32 v71, v0
	v_mov_b32_e32 v80, v0
	v_mov_b32_e32 v81, v0
	v_mov_b32_e32 v82, v0
	v_mov_b32_e32 v83, v0
	v_mov_b32_e32 v84, v0
	v_mov_b32_e32 v85, v0
	v_mov_b32_e32 v86, v0
	v_mov_b32_e32 v87, v0
	v_mov_b32_e32 v96, v0
	v_mov_b32_e32 v97, v0
	v_mov_b32_e32 v98, v0
	v_mov_b32_e32 v99, v0
	v_mov_b32_e32 v100, v0
	v_mov_b32_e32 v101, v0
	v_mov_b32_e32 v102, v0
	v_mov_b32_e32 v103, v0
	v_mov_b32_e32 v112, v0
	v_mov_b32_e32 v113, v0
	v_mov_b32_e32 v114, v0
	v_mov_b32_e32 v115, v0
	v_mov_b32_e32 v116, v0
	v_mov_b32_e32 v117, v0
	v_mov_b32_e32 v118, v0
	v_mov_b32_e32 v119, v0
	v_mov_b32_e32 v72, v0
	v_mov_b32_e32 v73, v0
	v_mov_b32_e32 v74, v0
	v_mov_b32_e32 v75, v0
	v_mov_b32_e32 v76, v0
	v_mov_b32_e32 v77, v0
	v_mov_b32_e32 v78, v0
	v_mov_b32_e32 v79, v0
	v_mov_b32_e32 v88, v0
	v_mov_b32_e32 v89, v0
	v_mov_b32_e32 v90, v0
	v_mov_b32_e32 v91, v0
	v_mov_b32_e32 v92, v0
	v_mov_b32_e32 v93, v0
	v_mov_b32_e32 v94, v0
	v_mov_b32_e32 v95, v0
	v_mov_b32_e32 v104, v0
	v_mov_b32_e32 v105, v0
	v_mov_b32_e32 v106, v0
	v_mov_b32_e32 v107, v0
	v_mov_b32_e32 v108, v0
	v_mov_b32_e32 v109, v0
	v_mov_b32_e32 v110, v0
	v_mov_b32_e32 v111, v0
	v_mov_b32_e32 v120, v0
	v_mov_b32_e32 v121, v0
	v_mov_b32_e32 v122, v0
	v_mov_b32_e32 v123, v0
	v_mov_b32_e32 v124, v0
	v_mov_b32_e32 v125, v0
	v_mov_b32_e32 v126, v0
	v_mov_b32_e32 v127, v0
	v_lshl_add_u32 v240, s35, 8, v142
	v_ashrrev_i32_e32 v241, 31, v240
	v_lshl_add_u64 v[240:241], v[240:241], 2, s[88:89]
	global_load_dword v242, v[240:241], off
	global_load_dword v243, v[240:241], off offset:64
	global_load_dword v244, v[240:241], off offset:128
	global_load_dword v245, v[240:241], off offset:192
	global_load_dword v246, v[240:241], off offset:512
	global_load_dword v247, v[240:241], off offset:576
	global_load_dword v248, v[240:241], off offset:640
	global_load_dword v249, v[240:241], off offset:704

; __device__ __forceinline__ unsigned cvt_pk_bf16(float lo, float hi) { unsigned r; asm volatile("v_cvt_pk_bf16_f32 %0, %1, %2" : "=v"(r) : "v"(lo), "v"(hi)); return r; }
;     __device__ __forceinline__ void operator()(const f32x4 (&acc)[2][2][4][2], const Unit& u, int wr, int wc, int fr, int fq) const {
;     ...
;             for (int m = 0; m < 4; ++m) { bf16_t* rowp = O + (size_t)(row0 + ai * HALF + m * 16) * ldc + col0;
;                 float rsc = sc; if (rsmode == 1) { const float r_ = rs[row0 + ai * HALF + m * 16]; rsc = sc * (ACT == 2 ? r_ * r_ : r_); }
; #pragma unroll
;                 for (int bj = 0; bj < 2; ++bj) { f32x4 v0 = acc[ai][bj][m][0], v1 = acc[ai][bj][m][1];
;                     if (ACT == 2) {
; #pragma unroll
;                         for (int e = 0; e < 4; ++e) { const float a0 = fmaxf(v0[e], 0.f), a1 = fmaxf(v1[e], 0.f); v0[e] = a0 * a0; v1[e] = a1 * a1; } }
;                     v0 = v0 * cs[bj][0] * rsc; v1 = v1 * cs[bj][1] * rsc; u32x4 w; w.x = cvt_pk_bf16(v0[0], v0[1]); w.y = cvt_pk_bf16(v0[2], v0[3]); w.z = cvt_pk_bf16(v1[0], v1[1]); w.w = cvt_pk_bf16(v1[2], v1[3]);
;                     *(u32x4*)(rowp + bj * HALF) = w; } }
.LBB0_608:
	v_lshl_add_u32 v140, s35, 8, v142
	v_ashrrev_i32_e32 v141, 31, v140
	v_lshl_add_u64 v[138:139], v[140:141], 2, s[88:89]
	s_nop 0
	v_lshl_or_b32 v146, s34, 8, v144
	v_max_f32_e32 v152, v118, v118
	v_max_f32_e32 v153, v119, v119
	v_max_f32_e32 v118, 0, v126
	v_max_f32_e32 v119, 0, v127
	v_max_f32_e32 v148, v116, v116
	v_max_f32_e32 v149, v112, v112
	v_max_f32_e32 v150, v117, v117
	v_max_f32_e32 v151, v113, v113
	v_ashrrev_i32_e32 v147, 31, v146
	v_max_f32_e32 v112, 0, v124
	v_max_f32_e32 v116, 0, v120
	v_max_f32_e32 v113, 0, v125
	v_max_f32_e32 v117, 0, v121
	v_max_f32_e32 v120, 0, v122
	v_max_f32_e32 v121, 0, v123
	v_max_f32_e32 v126, 0, v152
	v_max_f32_e32 v127, 0, v153
	v_lshlrev_b64 v[152:153], 14, v[140:141]
	v_pk_mul_f32 v[118:119], v[118:119], v[118:119]
	v_max_f32_e32 v122, 0, v148
	v_max_f32_e32 v124, 0, v149
	v_max_f32_e32 v123, 0, v150
	v_max_f32_e32 v125, 0, v151
	v_max_f32_e32 v148, 0, v114
	v_max_f32_e32 v149, 0, v115
	v_or_b32_e32 v150, 16, v140
	v_lshlrev_b64 v[114:115], 1, v[146:147]
	v_pk_mul_f32 v[146:147], v[112:113], v[112:113]
	v_pk_mul_f32 v[116:117], v[116:117], v[116:117]
	v_pk_mul_f32 v[120:121], v[120:121], v[120:121]
	v_lshl_add_u64 v[112:113], s[72:73], 0, v[152:153]
	v_pk_mul_f32 v[122:123], v[122:123], v[122:123]
	v_pk_mul_f32 v[126:127], v[126:127], v[126:127]
	v_pk_mul_f32 v[124:125], v[124:125], v[124:125]
	v_pk_mul_f32 v[148:149], v[148:149], v[148:149]
	v_ashrrev_i32_e32 v151, 31, v150
	v_lshl_add_u64 v[112:113], v[112:113], 0, v[114:115]
	v_lshl_add_u64 v[152:153], v[150:151], 2, s[88:89]
	v_mul_f32_e32 v154, v242, v242
	v_pk_mul_f32 v[118:119], v[118:119], v[154:155] op_sel_hi:[1,0]
	v_pk_mul_f32 v[146:147], v[146:147], v[154:155] op_sel_hi:[1,0]
	v_pk_mul_f32 v[120:121], v[120:121], v[154:155] op_sel_hi:[1,0]
	v_pk_mul_f32 v[156:157], v[116:117], v[154:155] op_sel_hi:[1,0]
	v_cvt_pk_bf16_f32 v116, v146, v147
	v_cvt_pk_bf16_f32 v117, v118, v119
	v_pk_mul_f32 v[126:127], v[126:127], v[154:155] op_sel_hi:[1,0]
	v_cvt_pk_bf16_f32 v118, v156, v157
	v_cvt_pk_bf16_f32 v119, v120, v121
	v_pk_mul_f32 v[122:123], v[122:123], v[154:155] op_sel_hi:[1,0]
	v_pk_mul_f32 v[148:149], v[148:149], v[154:155] op_sel_hi:[1,0]
	v_pk_mul_f32 v[124:125], v[124:125], v[154:155] op_sel_hi:[1,0]
	global_store_dwordx4 v[112:113], v[116:119], off
	v_max_f32_e32 v121, v98, v98
	v_max_f32_e32 v98, 0, v104
	v_cvt_pk_bf16_f32 v116, v122, v123
	v_cvt_pk_bf16_f32 v117, v126, v127
	v_cvt_pk_bf16_f32 v118, v124, v125
	v_cvt_pk_bf16_f32 v119, v148, v149
	global_store_dwordx4 v[112:113], v[116:119], off offset:256
	s_nop 0
	v_max_f32_e32 v124, v99, v99
	v_max_f32_e32 v117, v96, v96
	v_max_f32_e32 v118, v101, v101
	v_max_f32_e32 v119, v97, v97
	v_max_f32_e32 v96, 0, v108
	v_max_f32_e32 v97, 0, v109
	v_max_f32_e32 v99, 0, v105
	v_max_f32_e32 v116, v100, v100
	v_max_f32_e32 v120, v102, v102
	v_max_f32_e32 v123, v103, v103
	v_max_f32_e32 v100, 0, v110
	v_max_f32_e32 v102, 0, v106
	v_max_f32_e32 v101, 0, v111
	v_max_f32_e32 v103, 0, v107
	v_max_f32_e32 v105, 0, v118
	v_max_f32_e32 v107, 0, v119
	v_pk_mul_f32 v[96:97], v[96:97], v[96:97]
	v_pk_mul_f32 v[98:99], v[98:99], v[98:99]
	v_lshlrev_b64 v[118:119], 14, v[150:151]
	v_max_f32_e32 v104, 0, v116
	v_max_f32_e32 v106, 0, v117
	v_max_f32_e32 v108, 0, v120
	v_max_f32_e32 v110, 0, v121
	v_max_f32_e32 v109, 0, v123
	v_max_f32_e32 v111, 0, v124
	v_or_b32_e32 v116, 32, v140
	v_pk_mul_f32 v[100:101], v[100:101], v[100:101]
	v_pk_mul_f32 v[102:103], v[102:103], v[102:103]
	v_lshl_add_u64 v[118:119], s[72:73], 0, v[118:119]
	v_pk_mul_f32 v[104:105], v[104:105], v[104:105]
	v_pk_mul_f32 v[108:109], v[108:109], v[108:109]
	v_pk_mul_f32 v[106:107], v[106:107], v[106:107]
	v_pk_mul_f32 v[110:111], v[110:111], v[110:111]
	v_ashrrev_i32_e32 v117, 31, v116
	v_lshl_add_u64 v[118:119], v[118:119], 0, v[114:115]
	v_lshl_add_u64 v[120:121], v[116:117], 2, s[88:89]
	s_mov_b32 s7, 0x200000
	s_mov_b64 s[8:9], 0x200000
	v_mul_f32_e32 v122, v243, v243
	v_pk_mul_f32 v[96:97], v[96:97], v[122:123] op_sel_hi:[1,0]
	v_pk_mul_f32 v[98:99], v[98:99], v[122:123] op_sel_hi:[1,0]
	v_pk_mul_f32 v[100:101], v[100:101], v[122:123] op_sel_hi:[1,0]
	v_pk_mul_f32 v[102:103], v[102:103], v[122:123] op_sel_hi:[1,0]
	v_cvt_pk_bf16_f32 v96, v96, v97
	v_cvt_pk_bf16_f32 v97, v100, v101
	v_cvt_pk_bf16_f32 v98, v98, v99
	v_pk_mul_f32 v[108:109], v[108:109], v[122:123] op_sel_hi:[1,0]
	v_cvt_pk_bf16_f32 v99, v102, v103
	v_pk_mul_f32 v[104:105], v[104:105], v[122:123] op_sel_hi:[1,0]
	v_pk_mul_f32 v[110:111], v[110:111], v[122:123] op_sel_hi:[1,0]
	v_pk_mul_f32 v[106:107], v[106:107], v[122:123] op_sel_hi:[1,0]
	global_store_dwordx4 v[118:119], v[96:99], off
	v_max_f32_e32 v101, v82, v82
	v_max_f32_e32 v82, 0, v88
	v_cvt_pk_bf16_f32 v96, v104, v105
	v_cvt_pk_bf16_f32 v97, v108, v109
	v_cvt_pk_bf16_f32 v98, v106, v107
	v_cvt_pk_bf16_f32 v99, v110, v111
	global_store_dwordx4 v[118:119], v[96:99], off offset:256
	s_nop 0
	v_max_f32_e32 v104, v83, v83
	v_max_f32_e32 v97, v80, v80
	v_max_f32_e32 v98, v85, v85
	v_max_f32_e32 v99, v81, v81
	v_max_f32_e32 v80, 0, v92
	v_max_f32_e32 v81, 0, v93
	v_max_f32_e32 v83, 0, v89
	v_max_f32_e32 v96, v84, v84
	v_max_f32_e32 v100, v86, v86
	v_max_f32_e32 v103, v87, v87
	v_max_f32_e32 v84, 0, v94
	v_max_f32_e32 v86, 0, v90
	v_max_f32_e32 v85, 0, v95
	v_max_f32_e32 v87, 0, v91
	v_max_f32_e32 v89, 0, v98
	v_max_f32_e32 v91, 0, v99
	v_pk_mul_f32 v[80:81], v[80:81], v[80:81]
	v_pk_mul_f32 v[82:83], v[82:83], v[82:83]
	v_lshlrev_b64 v[98:99], 14, v[116:117]
	v_max_f32_e32 v88, 0, v96
	v_max_f32_e32 v90, 0, v97
	v_max_f32_e32 v92, 0, v100
	v_max_f32_e32 v94, 0, v101
	v_max_f32_e32 v93, 0, v103
; __device__ __forceinline__ unsigned cvt_pk_bf16(float lo, float hi) { unsigned r; asm volatile("v_cvt_pk_bf16_f32 %0, %1, %2" : "=v"(r) : "v"(lo), "v"(hi)); return r; }
;     __device__ __forceinline__ void operator()(const f32x4 (&acc)[2][2][4][2], const Unit& u, int wr, int wc, int fr, int fq) const {
;     ...
;             for (int m = 0; m < 4; ++m) { bf16_t* rowp = O + (size_t)(row0 + ai * HALF + m * 16) * ldc + col0;
;                 float rsc = sc; if (rsmode == 1) { const float r_ = rs[row0 + ai * HALF + m * 16]; rsc = sc * (ACT == 2 ? r_ * r_ : r_); }
; #pragma unroll
;                 for (int bj = 0; bj < 2; ++bj) { f32x4 v0 = acc[ai][bj][m][0], v1 = acc[ai][bj][m][1];
;                     if (ACT == 2) {
; #pragma unroll
;                         for (int e = 0; e < 4; ++e) { const float a0 = fmaxf(v0[e], 0.f), a1 = fmaxf(v1[e], 0.f); v0[e] = a0 * a0; v1[e] = a1 * a1; } }
;                     v0 = v0 * cs[bj][0] * rsc; v1 = v1 * cs[bj][1] * rsc; u32x4 w; w.x = cvt_pk_bf16(v0[0], v0[1]); w.y = cvt_pk_bf16(v0[2], v0[3]); w.z = cvt_pk_bf16(v1[0], v1[1]); w.w = cvt_pk_bf16(v1[2], v1[3]);
;                     *(u32x4*)(rowp + bj * HALF) = w; } }
	v_max_f32_e32 v95, 0, v104
	v_or_b32_e32 v96, 48, v140
	v_pk_mul_f32 v[84:85], v[84:85], v[84:85]
	v_pk_mul_f32 v[86:87], v[86:87], v[86:87]
	v_lshl_add_u64 v[98:99], s[72:73], 0, v[98:99]
	v_pk_mul_f32 v[88:89], v[88:89], v[88:89]
	v_pk_mul_f32 v[92:93], v[92:93], v[92:93]
	v_pk_mul_f32 v[90:91], v[90:91], v[90:91]
	v_pk_mul_f32 v[94:95], v[94:95], v[94:95]
	v_ashrrev_i32_e32 v97, 31, v96
	v_lshl_add_u64 v[98:99], v[98:99], 0, v[114:115]
	v_lshl_add_u64 v[100:101], v[96:97], 2, s[88:89]
	v_mul_f32_e32 v102, v244, v244
	v_pk_mul_f32 v[80:81], v[80:81], v[102:103] op_sel_hi:[1,0]
	v_pk_mul_f32 v[82:83], v[82:83], v[102:103] op_sel_hi:[1,0]
	v_pk_mul_f32 v[84:85], v[84:85], v[102:103] op_sel_hi:[1,0]
	v_pk_mul_f32 v[86:87], v[86:87], v[102:103] op_sel_hi:[1,0]
	v_cvt_pk_bf16_f32 v80, v80, v81
	v_cvt_pk_bf16_f32 v81, v84, v85
	v_cvt_pk_bf16_f32 v82, v82, v83
	v_pk_mul_f32 v[92:93], v[92:93], v[102:103] op_sel_hi:[1,0]
	v_cvt_pk_bf16_f32 v83, v86, v87
	v_pk_mul_f32 v[88:89], v[88:89], v[102:103] op_sel_hi:[1,0]
	v_pk_mul_f32 v[94:95], v[94:95], v[102:103] op_sel_hi:[1,0]
	v_pk_mul_f32 v[90:91], v[90:91], v[102:103] op_sel_hi:[1,0]
	global_store_dwordx4 v[98:99], v[80:83], off
	v_max_f32_e32 v84, v65, v65
	v_max_f32_e32 v86, v66, v66
	v_cvt_pk_bf16_f32 v80, v88, v89
	v_cvt_pk_bf16_f32 v81, v92, v93
	v_cvt_pk_bf16_f32 v82, v90, v91
	v_cvt_pk_bf16_f32 v83, v94, v95
	global_store_dwordx4 v[98:99], v[80:83], off offset:256
	s_nop 0
	v_max_f32_e32 v88, v67, v67
	v_max_f32_e32 v80, v68, v68
	v_max_f32_e32 v81, v64, v64
	v_max_f32_e32 v64, 0, v76
	v_max_f32_e32 v66, 0, v72
	v_max_f32_e32 v65, 0, v77
	v_max_f32_e32 v67, 0, v73
	v_max_f32_e32 v83, v69, v69
	v_max_f32_e32 v85, v70, v70
	v_max_f32_e32 v87, v71, v71
	v_max_f32_e32 v68, 0, v78
	v_max_f32_e32 v70, 0, v74
	v_max_f32_e32 v69, 0, v79
	v_max_f32_e32 v71, 0, v75
	v_max_f32_e32 v72, 0, v80
	v_max_f32_e32 v74, 0, v81
	v_pk_mul_f32 v[64:65], v[64:65], v[64:65]
	v_pk_mul_f32 v[66:67], v[66:67], v[66:67]
	v_lshlrev_b64 v[80:81], 14, v[96:97]
	v_max_f32_e32 v73, 0, v83
	v_max_f32_e32 v75, 0, v84
	v_max_f32_e32 v76, 0, v85
	v_max_f32_e32 v78, 0, v86
	v_max_f32_e32 v77, 0, v87
	v_max_f32_e32 v79, 0, v88
	v_pk_mul_f32 v[68:69], v[68:69], v[68:69]
	v_pk_mul_f32 v[70:71], v[70:71], v[70:71]
	v_lshl_add_u64 v[80:81], s[72:73], 0, v[80:81]
	v_pk_mul_f32 v[72:73], v[72:73], v[72:73]
	v_pk_mul_f32 v[76:77], v[76:77], v[76:77]
	v_pk_mul_f32 v[74:75], v[74:75], v[74:75]
	v_pk_mul_f32 v[78:79], v[78:79], v[78:79]
	v_lshl_add_u64 v[80:81], v[80:81], 0, v[114:115]
	v_mul_f32_e32 v82, v245, v245
	v_pk_mul_f32 v[64:65], v[64:65], v[82:83] op_sel_hi:[1,0]
	v_pk_mul_f32 v[66:67], v[66:67], v[82:83] op_sel_hi:[1,0]
	v_pk_mul_f32 v[68:69], v[68:69], v[82:83] op_sel_hi:[1,0]
	v_pk_mul_f32 v[70:71], v[70:71], v[82:83] op_sel_hi:[1,0]
	v_cvt_pk_bf16_f32 v64, v64, v65
	v_cvt_pk_bf16_f32 v65, v68, v69
	v_cvt_pk_bf16_f32 v66, v66, v67
	v_pk_mul_f32 v[76:77], v[76:77], v[82:83] op_sel_hi:[1,0]
	v_cvt_pk_bf16_f32 v67, v70, v71
	v_pk_mul_f32 v[72:73], v[72:73], v[82:83] op_sel_hi:[1,0]
	v_pk_mul_f32 v[78:79], v[78:79], v[82:83] op_sel_hi:[1,0]
	v_pk_mul_f32 v[74:75], v[74:75], v[82:83] op_sel_hi:[1,0]
	global_store_dwordx4 v[80:81], v[64:67], off
	v_max_f32_e32 v70, v50, v50
	v_max_f32_e32 v50, 0, v56
	v_cvt_pk_bf16_f32 v64, v72, v73
	v_cvt_pk_bf16_f32 v65, v76, v77
	v_cvt_pk_bf16_f32 v66, v74, v75
	v_cvt_pk_bf16_f32 v67, v78, v79
	global_store_dwordx4 v[80:81], v[64:67], off offset:256
	s_nop 0
	v_max_f32_e32 v72, v51, v51
	v_max_f32_e32 v65, v48, v48
	v_max_f32_e32 v67, v49, v49
	v_max_f32_e32 v48, 0, v60
	v_max_f32_e32 v49, 0, v61
	v_max_f32_e32 v51, 0, v57
	v_max_f32_e32 v64, v52, v52
	v_max_f32_e32 v66, v53, v53
	v_max_f32_e32 v69, v54, v54
	v_max_f32_e32 v71, v55, v55
	v_max_f32_e32 v52, 0, v62
	v_max_f32_e32 v54, 0, v58
	v_max_f32_e32 v53, 0, v63
	v_max_f32_e32 v55, 0, v59
	v_pk_mul_f32 v[48:49], v[48:49], v[48:49]
	v_pk_mul_f32 v[50:51], v[50:51], v[50:51]
	v_max_f32_e32 v56, 0, v64
	v_max_f32_e32 v58, 0, v65
	v_max_f32_e32 v57, 0, v66
	v_max_f32_e32 v59, 0, v67
	v_max_f32_e32 v60, 0, v69
	v_max_f32_e32 v62, 0, v70
	v_max_f32_e32 v61, 0, v71
	v_max_f32_e32 v63, 0, v72
	v_pk_mul_f32 v[52:53], v[52:53], v[52:53]
	v_pk_mul_f32 v[54:55], v[54:55], v[54:55]
	v_add_co_u32_e32 v66, vcc, s7, v112
	v_pk_mul_f32 v[56:57], v[56:57], v[56:57]
	v_pk_mul_f32 v[60:61], v[60:61], v[60:61]
	v_pk_mul_f32 v[58:59], v[58:59], v[58:59]
	v_pk_mul_f32 v[62:63], v[62:63], v[62:63]
	v_lshl_add_u64 v[64:65], v[112:113], 0, s[8:9]
	v_addc_co_u32_e32 v67, vcc, 0, v113, vcc
	s_mov_b32 s7, 0x240000
	s_mov_b64 s[8:9], 0x240000
	v_mul_f32_e32 v68, v246, v246
	v_pk_mul_f32 v[48:49], v[48:49], v[68:69] op_sel_hi:[1,0]
	v_pk_mul_f32 v[50:51], v[50:51], v[68:69] op_sel_hi:[1,0]
	v_pk_mul_f32 v[52:53], v[52:53], v[68:69] op_sel_hi:[1,0]
	v_pk_mul_f32 v[54:55], v[54:55], v[68:69] op_sel_hi:[1,0]
	v_cvt_pk_bf16_f32 v48, v48, v49
	v_cvt_pk_bf16_f32 v49, v52, v53
	v_cvt_pk_bf16_f32 v50, v50, v51
	v_pk_mul_f32 v[60:61], v[60:61], v[68:69] op_sel_hi:[1,0]
	v_cvt_pk_bf16_f32 v51, v54, v55
	v_pk_mul_f32 v[56:57], v[56:57], v[68:69] op_sel_hi:[1,0]
	v_pk_mul_f32 v[62:63], v[62:63], v[68:69] op_sel_hi:[1,0]
	v_pk_mul_f32 v[58:59], v[58:59], v[68:69] op_sel_hi:[1,0]
	global_store_dwordx4 v[66:67], v[48:51], off
	v_max_f32_e32 v54, v34, v34
	v_max_f32_e32 v34, 0, v40
	v_cvt_pk_bf16_f32 v48, v56, v57
	v_cvt_pk_bf16_f32 v49, v60, v61
	v_cvt_pk_bf16_f32 v50, v58, v59
	v_cvt_pk_bf16_f32 v51, v62, v63
	global_store_dwordx4 v[64:65], v[48:51], off offset:256
	s_nop 0
	v_max_f32_e32 v56, v35, v35
	v_max_f32_e32 v49, v32, v32
	v_max_f32_e32 v51, v33, v33
	v_max_f32_e32 v32, 0, v44
; __device__ __forceinline__ unsigned cvt_pk_bf16(float lo, float hi) { unsigned r; asm volatile("v_cvt_pk_bf16_f32 %0, %1, %2" : "=v"(r) : "v"(lo), "v"(hi)); return r; }
;     __device__ __forceinline__ void operator()(const f32x4 (&acc)[2][2][4][2], const Unit& u, int wr, int wc, int fr, int fq) const {
;     ...
;             for (int m = 0; m < 4; ++m) { bf16_t* rowp = O + (size_t)(row0 + ai * HALF + m * 16) * ldc + col0;
;                 float rsc = sc; if (rsmode == 1) { const float r_ = rs[row0 + ai * HALF + m * 16]; rsc = sc * (ACT == 2 ? r_ * r_ : r_); }
; #pragma unroll
;                 for (int bj = 0; bj < 2; ++bj) { f32x4 v0 = acc[ai][bj][m][0], v1 = acc[ai][bj][m][1];
;                     if (ACT == 2) {
; #pragma unroll
;                         for (int e = 0; e < 4; ++e) { const float a0 = fmaxf(v0[e], 0.f), a1 = fmaxf(v1[e], 0.f); v0[e] = a0 * a0; v1[e] = a1 * a1; } }
;                     v0 = v0 * cs[bj][0] * rsc; v1 = v1 * cs[bj][1] * rsc; u32x4 w; w.x = cvt_pk_bf16(v0[0], v0[1]); w.y = cvt_pk_bf16(v0[2], v0[3]); w.z = cvt_pk_bf16(v1[0], v1[1]); w.w = cvt_pk_bf16(v1[2], v1[3]);
;                     *(u32x4*)(rowp + bj * HALF) = w; } }
	v_max_f32_e32 v33, 0, v45
	v_max_f32_e32 v35, 0, v41
	v_max_f32_e32 v48, v36, v36
	v_max_f32_e32 v50, v37, v37
	v_max_f32_e32 v53, v38, v38
	v_max_f32_e32 v55, v39, v39
	v_max_f32_e32 v36, 0, v46
	v_max_f32_e32 v38, 0, v42
	v_max_f32_e32 v37, 0, v47
	v_max_f32_e32 v39, 0, v43
	v_pk_mul_f32 v[32:33], v[32:33], v[32:33]
	v_pk_mul_f32 v[34:35], v[34:35], v[34:35]
	v_max_f32_e32 v40, 0, v48
	v_max_f32_e32 v42, 0, v49
	v_max_f32_e32 v41, 0, v50
	v_max_f32_e32 v43, 0, v51
	v_max_f32_e32 v44, 0, v53
	v_max_f32_e32 v46, 0, v54
	v_max_f32_e32 v45, 0, v55
	v_max_f32_e32 v47, 0, v56
	v_pk_mul_f32 v[36:37], v[36:37], v[36:37]
	v_pk_mul_f32 v[38:39], v[38:39], v[38:39]
	v_add_co_u32_e32 v50, vcc, s7, v112
	v_pk_mul_f32 v[40:41], v[40:41], v[40:41]
	v_pk_mul_f32 v[44:45], v[44:45], v[44:45]
	v_pk_mul_f32 v[42:43], v[42:43], v[42:43]
	v_pk_mul_f32 v[46:47], v[46:47], v[46:47]
	v_lshl_add_u64 v[48:49], v[112:113], 0, s[8:9]
	v_addc_co_u32_e32 v51, vcc, 0, v113, vcc
	s_mov_b32 s7, 0x280000
	s_mov_b64 s[8:9], 0x280000
	v_mul_f32_e32 v52, v247, v247
	v_pk_mul_f32 v[32:33], v[32:33], v[52:53] op_sel_hi:[1,0]
	v_pk_mul_f32 v[34:35], v[34:35], v[52:53] op_sel_hi:[1,0]
	v_pk_mul_f32 v[36:37], v[36:37], v[52:53] op_sel_hi:[1,0]
	v_pk_mul_f32 v[38:39], v[38:39], v[52:53] op_sel_hi:[1,0]
	v_cvt_pk_bf16_f32 v32, v32, v33
	v_cvt_pk_bf16_f32 v33, v36, v37
	v_cvt_pk_bf16_f32 v34, v34, v35
	v_pk_mul_f32 v[44:45], v[44:45], v[52:53] op_sel_hi:[1,0]
	v_cvt_pk_bf16_f32 v35, v38, v39
	v_pk_mul_f32 v[40:41], v[40:41], v[52:53] op_sel_hi:[1,0]
	v_pk_mul_f32 v[46:47], v[46:47], v[52:53] op_sel_hi:[1,0]
	v_pk_mul_f32 v[42:43], v[42:43], v[52:53] op_sel_hi:[1,0]
	global_store_dwordx4 v[50:51], v[32:35], off
	v_max_f32_e32 v38, v18, v18
	v_max_f32_e32 v18, 0, v24
	v_cvt_pk_bf16_f32 v32, v40, v41
	v_cvt_pk_bf16_f32 v33, v44, v45
	v_cvt_pk_bf16_f32 v34, v42, v43
	v_cvt_pk_bf16_f32 v35, v46, v47
	global_store_dwordx4 v[48:49], v[32:35], off offset:256
	s_nop 0
	v_max_f32_e32 v40, v19, v19
	v_max_f32_e32 v33, v16, v16
	v_max_f32_e32 v35, v17, v17
	v_max_f32_e32 v16, 0, v28
	v_max_f32_e32 v17, 0, v29
	v_max_f32_e32 v19, 0, v25
	v_max_f32_e32 v32, v20, v20
	v_max_f32_e32 v34, v21, v21
	v_max_f32_e32 v37, v22, v22
	v_max_f32_e32 v39, v23, v23
	v_max_f32_e32 v20, 0, v30
	v_max_f32_e32 v22, 0, v26
	v_max_f32_e32 v21, 0, v31
	v_max_f32_e32 v23, 0, v27
	v_pk_mul_f32 v[16:17], v[16:17], v[16:17]
	v_pk_mul_f32 v[18:19], v[18:19], v[18:19]
	v_max_f32_e32 v24, 0, v32
	v_max_f32_e32 v26, 0, v33
	v_max_f32_e32 v25, 0, v34
	v_max_f32_e32 v27, 0, v35
	v_max_f32_e32 v28, 0, v37
	v_max_f32_e32 v30, 0, v38
	v_max_f32_e32 v29, 0, v39
	v_max_f32_e32 v31, 0, v40
	v_pk_mul_f32 v[20:21], v[20:21], v[20:21]
	v_pk_mul_f32 v[22:23], v[22:23], v[22:23]
	v_add_co_u32_e32 v34, vcc, s7, v112
	v_pk_mul_f32 v[24:25], v[24:25], v[24:25]
	v_pk_mul_f32 v[28:29], v[28:29], v[28:29]
	v_pk_mul_f32 v[26:27], v[26:27], v[26:27]
	v_pk_mul_f32 v[30:31], v[30:31], v[30:31]
	v_lshl_add_u64 v[32:33], v[112:113], 0, s[8:9]
	v_addc_co_u32_e32 v35, vcc, 0, v113, vcc
	s_mov_b32 s7, 0x2c0000
	s_andn2_b64 vcc, exec, s[42:43]
	s_mov_b64 s[8:9], 0x2c0000
	v_mul_f32_e32 v36, v248, v248
	v_pk_mul_f32 v[16:17], v[16:17], v[36:37] op_sel_hi:[1,0]
	v_pk_mul_f32 v[18:19], v[18:19], v[36:37] op_sel_hi:[1,0]
	v_pk_mul_f32 v[20:21], v[20:21], v[36:37] op_sel_hi:[1,0]
	v_pk_mul_f32 v[22:23], v[22:23], v[36:37] op_sel_hi:[1,0]
	v_cvt_pk_bf16_f32 v16, v16, v17
	v_cvt_pk_bf16_f32 v17, v20, v21
	v_cvt_pk_bf16_f32 v18, v18, v19
	v_pk_mul_f32 v[28:29], v[28:29], v[36:37] op_sel_hi:[1,0]
	v_cvt_pk_bf16_f32 v19, v22, v23
	v_pk_mul_f32 v[24:25], v[24:25], v[36:37] op_sel_hi:[1,0]
	v_pk_mul_f32 v[30:31], v[30:31], v[36:37] op_sel_hi:[1,0]
	v_pk_mul_f32 v[26:27], v[26:27], v[36:37] op_sel_hi:[1,0]
	global_store_dwordx4 v[34:35], v[16:19], off
	v_max_f32_e32 v22, v2, v2
	v_max_f32_e32 v2, 0, v8
	v_cvt_pk_bf16_f32 v16, v24, v25
	v_cvt_pk_bf16_f32 v17, v28, v29
	v_cvt_pk_bf16_f32 v18, v26, v27
	v_cvt_pk_bf16_f32 v19, v30, v31
	global_store_dwordx4 v[32:33], v[16:19], off offset:256
	s_nop 0
	v_max_f32_e32 v24, v3, v3
	v_max_f32_e32 v17, v0, v0
	v_max_f32_e32 v19, v1, v1
	v_max_f32_e32 v0, 0, v12
	v_max_f32_e32 v1, 0, v13
	v_max_f32_e32 v3, 0, v9
	v_max_f32_e32 v16, v4, v4
	v_max_f32_e32 v18, v5, v5
	v_max_f32_e32 v21, v6, v6
	v_max_f32_e32 v23, v7, v7
	v_max_f32_e32 v4, 0, v14
	v_max_f32_e32 v6, 0, v10
	v_max_f32_e32 v5, 0, v15
	v_max_f32_e32 v7, 0, v11
	v_pk_mul_f32 v[0:1], v[0:1], v[0:1]
	v_pk_mul_f32 v[2:3], v[2:3], v[2:3]
	v_max_f32_e32 v8, 0, v16
	v_max_f32_e32 v10, 0, v17
	v_max_f32_e32 v9, 0, v18
	v_max_f32_e32 v11, 0, v19
	v_max_f32_e32 v12, 0, v21
	v_max_f32_e32 v14, 0, v22
	v_max_f32_e32 v13, 0, v23
	v_max_f32_e32 v15, 0, v24
	v_pk_mul_f32 v[4:5], v[4:5], v[4:5]
	v_pk_mul_f32 v[6:7], v[6:7], v[6:7]
	v_add_co_u32_e64 v18, s[42:43], s7, v112
	v_pk_mul_f32 v[8:9], v[8:9], v[8:9]
	v_pk_mul_f32 v[12:13], v[12:13], v[12:13]
	v_pk_mul_f32 v[10:11], v[10:11], v[10:11]
	v_pk_mul_f32 v[14:15], v[14:15], v[14:15]
	v_lshl_add_u64 v[16:17], v[112:113], 0, s[8:9]
	v_addc_co_u32_e64 v19, s[42:43], 0, v113, s[42:43]
	s_mov_b64 s[8:9], -1
	v_mul_f32_e32 v20, v249, v249
	v_pk_mul_f32 v[0:1], v[0:1], v[20:21] op_sel_hi:[1,0]
	v_pk_mul_f32 v[2:3], v[2:3], v[20:21] op_sel_hi:[1,0]
	v_pk_mul_f32 v[4:5], v[4:5], v[20:21] op_sel_hi:[1,0]
	v_pk_mul_f32 v[6:7], v[6:7], v[20:21] op_sel_hi:[1,0]
	v_cvt_pk_bf16_f32 v0, v0, v1
	v_cvt_pk_bf16_f32 v1, v4, v5
	v_cvt_pk_bf16_f32 v2, v2, v3
	v_pk_mul_f32 v[12:13], v[12:13], v[20:21] op_sel_hi:[1,0]
	v_cvt_pk_bf16_f32 v3, v6, v7
	v_pk_mul_f32 v[8:9], v[8:9], v[20:21] op_sel_hi:[1,0]
	v_pk_mul_f32 v[14:15], v[14:15], v[20:21] op_sel_hi:[1,0]
	v_pk_mul_f32 v[10:11], v[10:11], v[20:21] op_sel_hi:[1,0]
	global_store_dwordx4 v[18:19], v[0:3], off
	s_nop 1
	v_cvt_pk_bf16_f32 v0, v8, v9
	v_cvt_pk_bf16_f32 v1, v12, v13
	v_cvt_pk_bf16_f32 v2, v10, v11
	v_cvt_pk_bf16_f32 v3, v14, v15
	global_store_dwordx4 v[16:17], v[0:3], off offset:256
	s_cbranch_vccnz .LBB0_597
	s_andn2_b64 vcc, exec, s[76:77]
	s_cbranch_vccnz .LBB0_596
	s_barrier
	s_branch .LBB0_596
